# P3 out-proj epilogue: the 16 in-place xb row stores made nontemporal (pre-drain L2 before the grid barrier's writeback), on top of P1 LDS tables + P2 pointer SALU
# speedup vs baseline: 1.0034x; 1.0003x over previous
; __device__ __forceinline__ unsigned cvt_pk_bf16(float lo, float hi) { unsigned r; asm volatile("v_cvt_pk_bf16_f32 %0, %1, %2" : "=v"(r) : "v"(lo), "v"(hi)); return r; }
;     __device__ __forceinline__ void operator()(const f32x4 (&acc)[2][2][4][2], const Unit& u, int wr, int wc, int fr, int fq) const {
;     ...
;         for (int ai = 0; ai < 2; ++ai)
; #pragma unroll
;             for (int m = 0; m < 4; ++m) { const int r = rowt + ai * HALF + wr * 64 + m * 16 + fr; const size_t off = (size_t)r * 1024 + col0; float ss = 0.f;
;                 float xi = 0.f; if constexpr (RECON) xi = xinv[r];
; #pragma unroll
;                 for (int bj = 0; bj < 2; ++bj) { f32x4 b0, b1;
;                     if constexpr (RECON) { const u32x4 w = *(const u32x4*)(xb + off + bj * HALF);
;                         b0 = (f32x4){__builtin_bit_cast(float, w.x << 16), __builtin_bit_cast(float, w.x & 0xffff0000u), __builtin_bit_cast(float, w.y << 16), __builtin_bit_cast(float, w.y & 0xffff0000u)} * xi * gi[bj][0];
;                         b1 = (f32x4){__builtin_bit_cast(float, w.z << 16), __builtin_bit_cast(float, w.z & 0xffff0000u), __builtin_bit_cast(float, w.w << 16), __builtin_bit_cast(float, w.w & 0xffff0000u)} * xi * gi[bj][1]; }
;                     else { b0 = *(const f32x4*)(base + off + bj * HALF); b1 = *(const f32x4*)(base + off + bj * HALF + 4); }
;                     const f32x4 o0 = b0 + acc[ai][bj][m][0], o1 = b1 + acc[ai][bj][m][1];
;                     ss += ((o0[0] * o0[0] + o0[1] * o0[1]) + (o0[2] * o0[2] + o0[3] * o0[3])) + ((o1[0] * o1[0] + o1[1] * o1[1]) + (o1[2] * o1[2] + o1[3] * o1[3]));
;                     u32x4 w2; w2.x = cvt_pk_bf16(o0[0], o0[1]); w2.y = cvt_pk_bf16(o0[2], o0[3]); w2.z = cvt_pk_bf16(o1[0], o1[1]); w2.w = cvt_pk_bf16(o1[2], o1[3]); *(u32x4*)(xb + off + bj * HALF) = w2; }
;                 ss += __shfl_xor(ss, 16); ss += __shfl_xor(ss, 32);
;                 if (fq == 0) stats[(size_t)r * 16 + u.pn * 4 + wc] = ss;
.LBB0_1233:
	v_lshl_or_b32 v144, s16, 8, v165
	v_lshl_add_u32 v154, s28, 8, v164
	v_ashrrev_i32_e32 v145, 31, v144
	v_ashrrev_i32_e32 v155, 31, v154
	v_lshl_add_u64 v[146:147], v[144:145], 2, s[48:49]
	v_lshlrev_b64 v[152:153], 11, v[154:155]
	global_load_dwordx4 v[148:151], v[146:147], off
	global_load_dwordx4 v[172:175], v[146:147], off offset:16
	v_lshl_add_u64 v[152:153], s[66:67], 0, v[152:153]
	v_lshl_add_u64 v[192:193], v[144:145], 1, v[152:153]
	global_load_dwordx4 v[176:179], v[192:193], off
	v_lshl_add_u64 v[152:153], v[154:155], 2, s[80:81]
	global_load_dword v194, v[152:153], off
	global_load_dwordx4 v[180:183], v[146:147], off offset:528
	global_load_dwordx4 v[184:187], v[146:147], off offset:512
	s_lshl_b32 s28, s16, 2
	s_ashr_i32 s29, s28, 31
	s_waitcnt vmcnt(0)
	v_rcp_f32_e32 v148, v148
	v_rcp_f32_e32 v149, v149
	v_rcp_f32_e32 v152, v150
	v_rcp_f32_e32 v153, v151
	v_rcp_f32_e32 v146, v172
	v_rcp_f32_e32 v147, v173
	v_rcp_f32_e32 v150, v174
	v_rcp_f32_e32 v151, v175
	v_lshlrev_b32_e32 v172, 16, v176
	v_and_b32_e32 v173, 0xffff0000, v176
	v_lshlrev_b32_e32 v174, 16, v177
	v_and_b32_e32 v175, 0xffff0000, v177
	v_lshlrev_b32_e32 v176, 16, v178
	v_and_b32_e32 v177, 0xffff0000, v178
	v_lshlrev_b32_e32 v178, 16, v179
	v_and_b32_e32 v179, 0xffff0000, v179
	v_pk_mul_f32 v[172:173], v[194:195], v[172:173] op_sel_hi:[0,1]
	v_pk_mul_f32 v[174:175], v[194:195], v[174:175] op_sel_hi:[0,1]
	v_pk_mul_f32 v[176:177], v[194:195], v[176:177] op_sel_hi:[0,1]
	v_pk_mul_f32 v[178:179], v[194:195], v[178:179] op_sel_hi:[0,1]
	v_pk_fma_f32 v[196:197], v[152:153], v[174:175], v[128:129]
	v_pk_fma_f32 v[198:199], v[148:149], v[172:173], v[126:127]
	v_pk_fma_f32 v[178:179], v[150:151], v[178:179], v[124:125]
	v_pk_fma_f32 v[200:201], v[146:147], v[176:177], v[122:123]
	v_cvt_pk_bf16_f32 v174, v198, v199
	v_cvt_pk_bf16_f32 v175, v196, v197
	v_and_b32_e32 v123, 64, v169
	v_cvt_pk_bf16_f32 v176, v200, v201
	v_cvt_pk_bf16_f32 v177, v178, v179
	global_load_dwordx4 v[188:191], v[192:193], off offset:256
	v_xor_b32_e32 v122, 16, v169
	v_add_u32_e32 v195, 64, v123
	v_cmp_lt_i32_e32 vcc, v122, v195
	v_rcp_f32_e32 v123, v181
	v_rcp_f32_e32 v126, v182
	v_cndmask_b32_e32 v122, v169, v122, vcc
	v_lshlrev_b32_e32 v172, 2, v122
	v_rcp_f32_e32 v122, v180
	v_mul_f32_e32 v180, v199, v199
	v_mul_f32_e32 v181, v197, v197
	v_mul_f32_e32 v182, v201, v201
	v_mul_f32_e32 v179, v179, v179
	v_rcp_f32_e32 v124, v184
	v_rcp_f32_e32 v125, v185
	v_rcp_f32_e32 v128, v186
	v_rcp_f32_e32 v129, v187
	v_rcp_f32_e32 v127, v183
	v_fmac_f32_e32 v180, v198, v198
	v_fmac_f32_e32 v181, v196, v196
	v_fmac_f32_e32 v182, v200, v200
	v_fmac_f32_e32 v179, v178, v178
	v_add_f32_e32 v178, v180, v181
	v_add_f32_e32 v179, v182, v179
	v_add_f32_e32 v186, v178, v179
	v_xor_b32_e32 v173, 32, v169
	v_cmp_lt_i32_e32 vcc, v173, v195
	global_store_dwordx4 v[192:193], v[174:177], off nt
	s_waitcnt vmcnt(1)
	v_lshlrev_b32_e32 v178, 16, v188
	v_and_b32_e32 v179, 0xffff0000, v188
	v_lshlrev_b32_e32 v180, 16, v189
	v_and_b32_e32 v181, 0xffff0000, v189
	v_lshlrev_b32_e32 v182, 16, v190
	v_and_b32_e32 v183, 0xffff0000, v190
	v_lshlrev_b32_e32 v184, 16, v191
	v_and_b32_e32 v185, 0xffff0000, v191
	v_pk_mul_f32 v[178:179], v[194:195], v[178:179] op_sel_hi:[0,1]
	v_pk_mul_f32 v[180:181], v[194:195], v[180:181] op_sel_hi:[0,1]
	v_pk_mul_f32 v[182:183], v[194:195], v[182:183] op_sel_hi:[0,1]
	v_pk_mul_f32 v[184:185], v[194:195], v[184:185] op_sel_hi:[0,1]
	v_pk_fma_f32 v[120:121], v[128:129], v[180:181], v[120:121]
	v_pk_fma_f32 v[118:119], v[124:125], v[178:179], v[118:119]
	v_pk_fma_f32 v[178:179], v[126:127], v[184:185], v[116:117]
	v_pk_fma_f32 v[180:181], v[122:123], v[182:183], v[114:115]
	v_mul_f32_e32 v114, v119, v119
	v_mul_f32_e32 v115, v121, v121
	v_mul_f32_e32 v116, v181, v181
	v_mul_f32_e32 v117, v179, v179
	v_fmac_f32_e32 v114, v118, v118
	v_fmac_f32_e32 v115, v120, v120
	v_fmac_f32_e32 v116, v180, v180
	v_fmac_f32_e32 v117, v178, v178
	v_add_f32_e32 v114, v114, v115
	v_add_f32_e32 v115, v116, v117
	v_add_f32_e32 v114, v114, v115
	v_add_f32_e32 v114, v186, v114
	ds_bpermute_b32 v115, v172, v114
	v_cndmask_b32_e32 v116, v169, v173, vcc
	v_lshlrev_b32_e32 v116, 2, v116
	v_cvt_pk_bf16_f32 v118, v118, v119
	v_cvt_pk_bf16_f32 v119, v120, v121
	s_waitcnt lgkmcnt(0)
	v_add_f32_e32 v114, v114, v115
	ds_bpermute_b32 v115, v116, v114
	v_cvt_pk_bf16_f32 v120, v180, v181
	v_cvt_pk_bf16_f32 v121, v178, v179
	global_store_dwordx4 v[192:193], v[118:121], off offset:256 nt
	s_and_saveexec_b64 s[30:31], s[6:7]
	s_cbranch_execz .LBB0_1235
	v_lshlrev_b64 v[118:119], 6, v[154:155]
	v_lshl_add_u64 v[118:119], s[8:9], 0, v[118:119]
	v_lshl_add_u64 v[118:119], s[28:29], 2, v[118:119]
	s_lshl_b32 s16, s53, 2
	v_lshl_add_u64 v[118:119], v[118:119], 0, s[16:17]
	s_waitcnt lgkmcnt(0)
	v_add_f32_e32 v114, v114, v115
	global_store_dword v[118:119], v114, off
; __device__ __forceinline__ unsigned cvt_pk_bf16(float lo, float hi) { unsigned r; asm volatile("v_cvt_pk_bf16_f32 %0, %1, %2" : "=v"(r) : "v"(lo), "v"(hi)); return r; }
;     __device__ __forceinline__ void operator()(const f32x4 (&acc)[2][2][4][2], const Unit& u, int wr, int wc, int fr, int fq) const {
;     ...
;             for (int m = 0; m < 4; ++m) { const int r = rowt + ai * HALF + wr * 64 + m * 16 + fr; const size_t off = (size_t)r * 1024 + col0; float ss = 0.f;
;                 float xi = 0.f; if constexpr (RECON) xi = xinv[r];
; #pragma unroll
;                 for (int bj = 0; bj < 2; ++bj) { f32x4 b0, b1;
;                     if constexpr (RECON) { const u32x4 w = *(const u32x4*)(xb + off + bj * HALF);
;                         b0 = (f32x4){__builtin_bit_cast(float, w.x << 16), __builtin_bit_cast(float, w.x & 0xffff0000u), __builtin_bit_cast(float, w.y << 16), __builtin_bit_cast(float, w.y & 0xffff0000u)} * xi * gi[bj][0];
;                         b1 = (f32x4){__builtin_bit_cast(float, w.z << 16), __builtin_bit_cast(float, w.z & 0xffff0000u), __builtin_bit_cast(float, w.w << 16), __builtin_bit_cast(float, w.w & 0xffff0000u)} * xi * gi[bj][1]; }
;                     else { b0 = *(const f32x4*)(base + off + bj * HALF); b1 = *(const f32x4*)(base + off + bj * HALF + 4); }
;                     const f32x4 o0 = b0 + acc[ai][bj][m][0], o1 = b1 + acc[ai][bj][m][1];
;                     ss += ((o0[0] * o0[0] + o0[1] * o0[1]) + (o0[2] * o0[2] + o0[3] * o0[3])) + ((o1[0] * o1[0] + o1[1] * o1[1]) + (o1[2] * o1[2] + o1[3] * o1[3]));
;                     u32x4 w2; w2.x = cvt_pk_bf16(o0[0], o0[1]); w2.y = cvt_pk_bf16(o0[2], o0[3]); w2.z = cvt_pk_bf16(o1[0], o1[1]); w2.w = cvt_pk_bf16(o1[2], o1[3]); *(u32x4*)(xb + off + bj * HALF) = w2; }
;                 ss += __shfl_xor(ss, 16); ss += __shfl_xor(ss, 32);
;                 if (fq == 0) stats[(size_t)r * 16 + u.pn * 4 + wc] = ss;
.LBB0_1235:
	s_or_b64 exec, exec, s[30:31]
	v_or_b32_e32 v114, 16, v154
	s_waitcnt lgkmcnt(0)
	v_ashrrev_i32_e32 v115, 31, v114
	v_lshlrev_b64 v[118:119], 11, v[114:115]
	v_lshl_add_u64 v[118:119], s[66:67], 0, v[118:119]
	v_lshl_add_u64 v[174:175], v[144:145], 1, v[118:119]
	global_load_dwordx4 v[118:121], v[174:175], off
	v_lshl_add_u64 v[176:177], v[114:115], 2, s[80:81]
	global_load_dword v176, v[176:177], off
	s_waitcnt vmcnt(1)
	v_lshlrev_b32_e32 v178, 16, v118
	v_and_b32_e32 v179, 0xffff0000, v118
	v_lshlrev_b32_e32 v118, 16, v119
	v_and_b32_e32 v119, 0xffff0000, v119
	v_lshlrev_b32_e32 v180, 16, v120
	v_and_b32_e32 v181, 0xffff0000, v120
	v_lshlrev_b32_e32 v120, 16, v121
	v_and_b32_e32 v121, 0xffff0000, v121
	s_waitcnt vmcnt(0)
	v_pk_mul_f32 v[178:179], v[176:177], v[178:179] op_sel_hi:[0,1]
	v_pk_mul_f32 v[118:119], v[176:177], v[118:119] op_sel_hi:[0,1]
	v_pk_mul_f32 v[180:181], v[176:177], v[180:181] op_sel_hi:[0,1]
	v_pk_mul_f32 v[120:121], v[176:177], v[120:121] op_sel_hi:[0,1]
	v_pk_fma_f32 v[118:119], v[152:153], v[118:119], v[112:113]
	v_pk_fma_f32 v[178:179], v[148:149], v[178:179], v[110:111]
	v_pk_fma_f32 v[120:121], v[150:151], v[120:121], v[108:109]
	v_pk_fma_f32 v[180:181], v[146:147], v[180:181], v[106:107]
	v_cvt_pk_bf16_f32 v106, v178, v179
	v_cvt_pk_bf16_f32 v107, v118, v119
	v_mul_f32_e32 v117, v179, v179
	v_cvt_pk_bf16_f32 v108, v180, v181
	v_cvt_pk_bf16_f32 v109, v120, v121
	global_load_dwordx4 v[110:113], v[174:175], off offset:256
	v_mul_f32_e32 v119, v119, v119
	v_mul_f32_e32 v155, v181, v181
	v_mul_f32_e32 v121, v121, v121
	v_fmac_f32_e32 v117, v178, v178
	v_fmac_f32_e32 v119, v118, v118
	v_fmac_f32_e32 v155, v180, v180
	v_fmac_f32_e32 v121, v120, v120
	v_add_f32_e32 v117, v117, v119
	v_add_f32_e32 v118, v155, v121
	v_add_f32_e32 v117, v117, v118
	global_store_dwordx4 v[174:175], v[106:109], off nt
	s_waitcnt vmcnt(1)
	v_lshlrev_b32_e32 v118, 16, v110
	v_and_b32_e32 v119, 0xffff0000, v110
	v_lshlrev_b32_e32 v110, 16, v111
	v_and_b32_e32 v111, 0xffff0000, v111
	v_lshlrev_b32_e32 v120, 16, v112
	v_and_b32_e32 v121, 0xffff0000, v112
	v_lshlrev_b32_e32 v112, 16, v113
	v_and_b32_e32 v113, 0xffff0000, v113
	v_pk_mul_f32 v[118:119], v[176:177], v[118:119] op_sel_hi:[0,1]
	v_pk_mul_f32 v[110:111], v[176:177], v[110:111] op_sel_hi:[0,1]
	v_pk_mul_f32 v[120:121], v[176:177], v[120:121] op_sel_hi:[0,1]
	v_pk_mul_f32 v[112:113], v[176:177], v[112:113] op_sel_hi:[0,1]
	v_pk_fma_f32 v[104:105], v[128:129], v[110:111], v[104:105]
	v_pk_fma_f32 v[102:103], v[124:125], v[118:119], v[102:103]
	v_pk_fma_f32 v[110:111], v[126:127], v[112:113], v[100:101]
	v_pk_fma_f32 v[112:113], v[122:123], v[120:121], v[98:99]
	v_mul_f32_e32 v98, v103, v103
	v_mul_f32_e32 v99, v105, v105
	v_mul_f32_e32 v100, v113, v113
	v_mul_f32_e32 v101, v111, v111
	v_fmac_f32_e32 v98, v102, v102
	v_fmac_f32_e32 v99, v104, v104
	v_fmac_f32_e32 v100, v112, v112
	v_fmac_f32_e32 v101, v110, v110
	v_add_f32_e32 v98, v98, v99
	v_add_f32_e32 v99, v100, v101
	v_add_f32_e32 v98, v98, v99
	v_add_f32_e32 v98, v117, v98
	ds_bpermute_b32 v99, v172, v98
	v_cvt_pk_bf16_f32 v100, v102, v103
	v_cvt_pk_bf16_f32 v101, v104, v105
	v_cvt_pk_bf16_f32 v102, v112, v113
	v_cvt_pk_bf16_f32 v103, v110, v111
	s_waitcnt lgkmcnt(0)
	v_add_f32_e32 v98, v98, v99
	ds_bpermute_b32 v99, v116, v98
	global_store_dwordx4 v[174:175], v[100:103], off offset:256 nt
	s_and_saveexec_b64 s[30:31], s[6:7]
	s_cbranch_execz .LBB0_1237
	v_lshlrev_b64 v[100:101], 6, v[114:115]
	v_lshl_add_u64 v[100:101], s[8:9], 0, v[100:101]
	v_lshl_add_u64 v[100:101], s[28:29], 2, v[100:101]
	s_lshl_b32 s16, s53, 2
	v_lshl_add_u64 v[100:101], v[100:101], 0, s[16:17]
	s_waitcnt lgkmcnt(0)
	v_add_f32_e32 v98, v98, v99
	global_store_dword v[100:101], v98, off
.LBB0_1237:
	s_or_b64 exec, exec, s[30:31]
	v_or_b32_e32 v98, 32, v154
	s_waitcnt lgkmcnt(0)
	v_ashrrev_i32_e32 v99, 31, v98
	v_lshlrev_b64 v[100:101], 11, v[98:99]
	v_lshl_add_u64 v[100:101], s[66:67], 0, v[100:101]
	v_lshl_add_u64 v[104:105], v[144:145], 1, v[100:101]
	global_load_dwordx4 v[100:103], v[104:105], off
	v_lshl_add_u64 v[106:107], v[98:99], 2, s[80:81]
	global_load_dword v106, v[106:107], off
	s_waitcnt vmcnt(1)
	v_lshlrev_b32_e32 v108, 16, v100
	v_and_b32_e32 v109, 0xffff0000, v100
	v_lshlrev_b32_e32 v100, 16, v101
	v_and_b32_e32 v101, 0xffff0000, v101
	v_lshlrev_b32_e32 v110, 16, v102
	v_and_b32_e32 v111, 0xffff0000, v102
	v_lshlrev_b32_e32 v102, 16, v103
	v_and_b32_e32 v103, 0xffff0000, v103
	s_waitcnt vmcnt(0)
	v_pk_mul_f32 v[108:109], v[106:107], v[108:109] op_sel_hi:[0,1]
	v_pk_mul_f32 v[100:101], v[106:107], v[100:101] op_sel_hi:[0,1]
	v_pk_mul_f32 v[110:111], v[106:107], v[110:111] op_sel_hi:[0,1]
	v_pk_mul_f32 v[102:103], v[106:107], v[102:103] op_sel_hi:[0,1]
	v_pk_fma_f32 v[100:101], v[152:153], v[100:101], v[96:97]
	v_pk_fma_f32 v[108:109], v[148:149], v[108:109], v[94:95]
	v_pk_fma_f32 v[102:103], v[150:151], v[102:103], v[92:93]
	v_pk_fma_f32 v[110:111], v[146:147], v[110:111], v[90:91]
	v_cvt_pk_bf16_f32 v90, v108, v109
	v_cvt_pk_bf16_f32 v91, v100, v101
	v_mul_f32_e32 v107, v109, v109
	v_cvt_pk_bf16_f32 v92, v110, v111
	v_cvt_pk_bf16_f32 v93, v102, v103
	global_load_dwordx4 v[94:97], v[104:105], off offset:256
	v_mul_f32_e32 v101, v101, v101
	v_mul_f32_e32 v109, v111, v111
	v_mul_f32_e32 v103, v103, v103
	v_fmac_f32_e32 v107, v108, v108
	v_fmac_f32_e32 v101, v100, v100
	v_fmac_f32_e32 v109, v110, v110
	v_fmac_f32_e32 v103, v102, v102
	v_add_f32_e32 v100, v107, v101
	v_add_f32_e32 v101, v109, v103
	v_add_f32_e32 v107, v100, v101
	global_store_dwordx4 v[104:105], v[90:93], off nt
	s_waitcnt vmcnt(1)
; __device__ __forceinline__ unsigned cvt_pk_bf16(float lo, float hi) { unsigned r; asm volatile("v_cvt_pk_bf16_f32 %0, %1, %2" : "=v"(r) : "v"(lo), "v"(hi)); return r; }
;     __device__ __forceinline__ void operator()(const f32x4 (&acc)[2][2][4][2], const Unit& u, int wr, int wc, int fr, int fq) const {
;     ...
;             for (int m = 0; m < 4; ++m) { const int r = rowt + ai * HALF + wr * 64 + m * 16 + fr; const size_t off = (size_t)r * 1024 + col0; float ss = 0.f;
;                 float xi = 0.f; if constexpr (RECON) xi = xinv[r];
; #pragma unroll
;                 for (int bj = 0; bj < 2; ++bj) { f32x4 b0, b1;
;                     if constexpr (RECON) { const u32x4 w = *(const u32x4*)(xb + off + bj * HALF);
;                         b0 = (f32x4){__builtin_bit_cast(float, w.x << 16), __builtin_bit_cast(float, w.x & 0xffff0000u), __builtin_bit_cast(float, w.y << 16), __builtin_bit_cast(float, w.y & 0xffff0000u)} * xi * gi[bj][0];
;                         b1 = (f32x4){__builtin_bit_cast(float, w.z << 16), __builtin_bit_cast(float, w.z & 0xffff0000u), __builtin_bit_cast(float, w.w << 16), __builtin_bit_cast(float, w.w & 0xffff0000u)} * xi * gi[bj][1]; }
;                     else { b0 = *(const f32x4*)(base + off + bj * HALF); b1 = *(const f32x4*)(base + off + bj * HALF + 4); }
;                     const f32x4 o0 = b0 + acc[ai][bj][m][0], o1 = b1 + acc[ai][bj][m][1];
;                     ss += ((o0[0] * o0[0] + o0[1] * o0[1]) + (o0[2] * o0[2] + o0[3] * o0[3])) + ((o1[0] * o1[0] + o1[1] * o1[1]) + (o1[2] * o1[2] + o1[3] * o1[3]));
;                     u32x4 w2; w2.x = cvt_pk_bf16(o0[0], o0[1]); w2.y = cvt_pk_bf16(o0[2], o0[3]); w2.z = cvt_pk_bf16(o1[0], o1[1]); w2.w = cvt_pk_bf16(o1[2], o1[3]); *(u32x4*)(xb + off + bj * HALF) = w2; }
;                 ss += __shfl_xor(ss, 16); ss += __shfl_xor(ss, 32);
;                 if (fq == 0) stats[(size_t)r * 16 + u.pn * 4 + wc] = ss;
	v_lshlrev_b32_e32 v100, 16, v94
	v_and_b32_e32 v101, 0xffff0000, v94
	v_lshlrev_b32_e32 v94, 16, v95
	v_and_b32_e32 v95, 0xffff0000, v95
	v_lshlrev_b32_e32 v102, 16, v96
	v_and_b32_e32 v103, 0xffff0000, v96
	v_lshlrev_b32_e32 v96, 16, v97
	v_and_b32_e32 v97, 0xffff0000, v97
	v_pk_mul_f32 v[100:101], v[106:107], v[100:101] op_sel_hi:[0,1]
	v_pk_mul_f32 v[94:95], v[106:107], v[94:95] op_sel_hi:[0,1]
	v_pk_mul_f32 v[102:103], v[106:107], v[102:103] op_sel_hi:[0,1]
	v_pk_mul_f32 v[96:97], v[106:107], v[96:97] op_sel_hi:[0,1]
	v_pk_fma_f32 v[88:89], v[128:129], v[94:95], v[88:89]
	v_pk_fma_f32 v[86:87], v[124:125], v[100:101], v[86:87]
	v_pk_fma_f32 v[94:95], v[126:127], v[96:97], v[84:85]
	v_pk_fma_f32 v[96:97], v[122:123], v[102:103], v[82:83]
	v_mul_f32_e32 v82, v87, v87
	v_mul_f32_e32 v83, v89, v89
	v_mul_f32_e32 v84, v97, v97
	v_mul_f32_e32 v85, v95, v95
	v_fmac_f32_e32 v82, v86, v86
	v_fmac_f32_e32 v83, v88, v88
	v_fmac_f32_e32 v84, v96, v96
	v_fmac_f32_e32 v85, v94, v94
	v_add_f32_e32 v82, v82, v83
	v_add_f32_e32 v83, v84, v85
	v_add_f32_e32 v82, v82, v83
	v_add_f32_e32 v82, v107, v82
	ds_bpermute_b32 v83, v172, v82
	v_cvt_pk_bf16_f32 v84, v86, v87
	v_cvt_pk_bf16_f32 v85, v88, v89
	v_cvt_pk_bf16_f32 v86, v96, v97
	v_cvt_pk_bf16_f32 v87, v94, v95
	s_waitcnt lgkmcnt(0)
	v_add_f32_e32 v82, v82, v83
	ds_bpermute_b32 v83, v116, v82
	global_store_dwordx4 v[104:105], v[84:87], off offset:256 nt
	s_and_saveexec_b64 s[30:31], s[6:7]
	s_cbranch_execz .LBB0_1239
	v_lshlrev_b64 v[84:85], 6, v[98:99]
	v_lshl_add_u64 v[84:85], s[8:9], 0, v[84:85]
	v_lshl_add_u64 v[84:85], s[28:29], 2, v[84:85]
	s_lshl_b32 s16, s53, 2
	v_lshl_add_u64 v[84:85], v[84:85], 0, s[16:17]
	s_waitcnt lgkmcnt(0)
	v_add_f32_e32 v82, v82, v83
	global_store_dword v[84:85], v82, off
.LBB0_1239:
	s_or_b64 exec, exec, s[30:31]
	v_or_b32_e32 v82, 48, v154
	s_waitcnt lgkmcnt(0)
	v_ashrrev_i32_e32 v83, 31, v82
	v_lshlrev_b64 v[84:85], 11, v[82:83]
	v_lshl_add_u64 v[84:85], s[66:67], 0, v[84:85]
	v_lshl_add_u64 v[88:89], v[144:145], 1, v[84:85]
	global_load_dwordx4 v[84:87], v[88:89], off
	v_lshl_add_u64 v[90:91], v[82:83], 2, s[80:81]
	global_load_dword v90, v[90:91], off
	s_waitcnt vmcnt(1)
	v_lshlrev_b32_e32 v92, 16, v84
	v_and_b32_e32 v93, 0xffff0000, v84
	v_lshlrev_b32_e32 v84, 16, v85
	v_and_b32_e32 v85, 0xffff0000, v85
	v_lshlrev_b32_e32 v94, 16, v86
	v_and_b32_e32 v95, 0xffff0000, v86
	v_lshlrev_b32_e32 v86, 16, v87
	v_and_b32_e32 v87, 0xffff0000, v87
	s_waitcnt vmcnt(0)
	v_pk_mul_f32 v[92:93], v[90:91], v[92:93] op_sel_hi:[0,1]
	v_pk_mul_f32 v[84:85], v[90:91], v[84:85] op_sel_hi:[0,1]
	v_pk_mul_f32 v[94:95], v[90:91], v[94:95] op_sel_hi:[0,1]
	v_pk_mul_f32 v[86:87], v[90:91], v[86:87] op_sel_hi:[0,1]
	v_pk_fma_f32 v[84:85], v[152:153], v[84:85], v[80:81]
	v_pk_fma_f32 v[92:93], v[148:149], v[92:93], v[78:79]
	v_pk_fma_f32 v[86:87], v[150:151], v[86:87], v[76:77]
	v_pk_fma_f32 v[94:95], v[146:147], v[94:95], v[74:75]
	v_cvt_pk_bf16_f32 v74, v92, v93
	v_cvt_pk_bf16_f32 v75, v84, v85
	v_mul_f32_e32 v91, v93, v93
	v_cvt_pk_bf16_f32 v76, v94, v95
	v_cvt_pk_bf16_f32 v77, v86, v87
	global_load_dwordx4 v[78:81], v[88:89], off offset:256
	v_mul_f32_e32 v85, v85, v85
	v_mul_f32_e32 v93, v95, v95
	v_mul_f32_e32 v87, v87, v87
	v_fmac_f32_e32 v91, v92, v92
	v_fmac_f32_e32 v85, v84, v84
	v_fmac_f32_e32 v93, v94, v94
	v_fmac_f32_e32 v87, v86, v86
	v_add_f32_e32 v84, v91, v85
	v_add_f32_e32 v85, v93, v87
	v_add_f32_e32 v91, v84, v85
	global_store_dwordx4 v[88:89], v[74:77], off nt
	s_waitcnt vmcnt(1)
	v_lshlrev_b32_e32 v84, 16, v78
	v_and_b32_e32 v85, 0xffff0000, v78
	v_lshlrev_b32_e32 v78, 16, v79
	v_and_b32_e32 v79, 0xffff0000, v79
	v_lshlrev_b32_e32 v86, 16, v80
	v_and_b32_e32 v87, 0xffff0000, v80
	v_lshlrev_b32_e32 v80, 16, v81
	v_and_b32_e32 v81, 0xffff0000, v81
	v_pk_mul_f32 v[84:85], v[90:91], v[84:85] op_sel_hi:[0,1]
	v_pk_mul_f32 v[78:79], v[90:91], v[78:79] op_sel_hi:[0,1]
	v_pk_mul_f32 v[86:87], v[90:91], v[86:87] op_sel_hi:[0,1]
	v_pk_mul_f32 v[80:81], v[90:91], v[80:81] op_sel_hi:[0,1]
	v_pk_fma_f32 v[72:73], v[128:129], v[78:79], v[72:73]
	v_pk_fma_f32 v[70:71], v[124:125], v[84:85], v[70:71]
	v_pk_fma_f32 v[78:79], v[126:127], v[80:81], v[68:69]
	v_pk_fma_f32 v[80:81], v[122:123], v[86:87], v[66:67]
	v_mul_f32_e32 v66, v71, v71
	v_mul_f32_e32 v67, v73, v73
	v_mul_f32_e32 v68, v81, v81
	v_mul_f32_e32 v69, v79, v79
	v_fmac_f32_e32 v66, v70, v70
	v_fmac_f32_e32 v67, v72, v72
	v_fmac_f32_e32 v68, v80, v80
	v_fmac_f32_e32 v69, v78, v78
	v_add_f32_e32 v66, v66, v67
	v_add_f32_e32 v67, v68, v69
	v_add_f32_e32 v66, v66, v67
	v_add_f32_e32 v66, v91, v66
	ds_bpermute_b32 v67, v172, v66
	v_cvt_pk_bf16_f32 v68, v70, v71
	v_cvt_pk_bf16_f32 v69, v72, v73
	v_cvt_pk_bf16_f32 v70, v80, v81
	v_cvt_pk_bf16_f32 v71, v78, v79
	s_waitcnt lgkmcnt(0)
	v_add_f32_e32 v66, v66, v67
	ds_bpermute_b32 v67, v116, v66
	global_store_dwordx4 v[88:89], v[68:71], off offset:256 nt
	s_and_saveexec_b64 s[30:31], s[6:7]
	s_cbranch_execz .LBB0_1241
	v_lshlrev_b64 v[68:69], 6, v[82:83]
	v_lshl_add_u64 v[68:69], s[8:9], 0, v[68:69]
	v_lshl_add_u64 v[68:69], s[28:29], 2, v[68:69]
	s_lshl_b32 s16, s53, 2
	v_lshl_add_u64 v[68:69], v[68:69], 0, s[16:17]
	s_waitcnt lgkmcnt(0)
	v_add_f32_e32 v66, v66, v67
	global_store_dword v[68:69], v66, off
; __device__ __forceinline__ unsigned cvt_pk_bf16(float lo, float hi) { unsigned r; asm volatile("v_cvt_pk_bf16_f32 %0, %1, %2" : "=v"(r) : "v"(lo), "v"(hi)); return r; }
;     __device__ __forceinline__ void operator()(const f32x4 (&acc)[2][2][4][2], const Unit& u, int wr, int wc, int fr, int fq) const {
;     ...
;         for (int ai = 0; ai < 2; ++ai)
; #pragma unroll
;             for (int m = 0; m < 4; ++m) { const int r = rowt + ai * HALF + wr * 64 + m * 16 + fr; const size_t off = (size_t)r * 1024 + col0; float ss = 0.f;
;                 float xi = 0.f; if constexpr (RECON) xi = xinv[r];
; #pragma unroll
;                 for (int bj = 0; bj < 2; ++bj) { f32x4 b0, b1;
;                     if constexpr (RECON) { const u32x4 w = *(const u32x4*)(xb + off + bj * HALF);
;                         b0 = (f32x4){__builtin_bit_cast(float, w.x << 16), __builtin_bit_cast(float, w.x & 0xffff0000u), __builtin_bit_cast(float, w.y << 16), __builtin_bit_cast(float, w.y & 0xffff0000u)} * xi * gi[bj][0];
;                         b1 = (f32x4){__builtin_bit_cast(float, w.z << 16), __builtin_bit_cast(float, w.z & 0xffff0000u), __builtin_bit_cast(float, w.w << 16), __builtin_bit_cast(float, w.w & 0xffff0000u)} * xi * gi[bj][1]; }
;                     else { b0 = *(const f32x4*)(base + off + bj * HALF); b1 = *(const f32x4*)(base + off + bj * HALF + 4); }
;                     const f32x4 o0 = b0 + acc[ai][bj][m][0], o1 = b1 + acc[ai][bj][m][1];
;                     ss += ((o0[0] * o0[0] + o0[1] * o0[1]) + (o0[2] * o0[2] + o0[3] * o0[3])) + ((o1[0] * o1[0] + o1[1] * o1[1]) + (o1[2] * o1[2] + o1[3] * o1[3]));
;                     u32x4 w2; w2.x = cvt_pk_bf16(o0[0], o0[1]); w2.y = cvt_pk_bf16(o0[2], o0[3]); w2.z = cvt_pk_bf16(o1[0], o1[1]); w2.w = cvt_pk_bf16(o1[2], o1[3]); *(u32x4*)(xb + off + bj * HALF) = w2; }
;                 ss += __shfl_xor(ss, 16); ss += __shfl_xor(ss, 32);
;                 if (fq == 0) stats[(size_t)r * 16 + u.pn * 4 + wc] = ss;
.LBB0_1241:
	s_or_b64 exec, exec, s[30:31]
	v_add_u32_e32 v66, 0x80, v154
	s_waitcnt lgkmcnt(0)
	v_ashrrev_i32_e32 v67, 31, v66
	v_lshlrev_b64 v[68:69], 11, v[66:67]
	v_lshl_add_u64 v[68:69], s[66:67], 0, v[68:69]
	v_lshl_add_u64 v[72:73], v[144:145], 1, v[68:69]
	global_load_dwordx4 v[68:71], v[72:73], off
	v_lshl_add_u64 v[74:75], v[66:67], 2, s[80:81]
	global_load_dword v74, v[74:75], off
	s_waitcnt vmcnt(1)
	v_lshlrev_b32_e32 v76, 16, v68
	v_and_b32_e32 v77, 0xffff0000, v68
	v_lshlrev_b32_e32 v68, 16, v69
	v_and_b32_e32 v69, 0xffff0000, v69
	v_lshlrev_b32_e32 v78, 16, v70
	v_and_b32_e32 v79, 0xffff0000, v70
	v_lshlrev_b32_e32 v70, 16, v71
	v_and_b32_e32 v71, 0xffff0000, v71
	s_waitcnt vmcnt(0)
	v_pk_mul_f32 v[76:77], v[74:75], v[76:77] op_sel_hi:[0,1]
	v_pk_mul_f32 v[68:69], v[74:75], v[68:69] op_sel_hi:[0,1]
	v_pk_mul_f32 v[78:79], v[74:75], v[78:79] op_sel_hi:[0,1]
	v_pk_mul_f32 v[70:71], v[74:75], v[70:71] op_sel_hi:[0,1]
	v_pk_fma_f32 v[68:69], v[152:153], v[68:69], v[64:65]
	v_pk_fma_f32 v[76:77], v[148:149], v[76:77], v[62:63]
	v_pk_fma_f32 v[70:71], v[150:151], v[70:71], v[60:61]
	v_pk_fma_f32 v[78:79], v[146:147], v[78:79], v[58:59]
	v_cvt_pk_bf16_f32 v58, v76, v77
	v_cvt_pk_bf16_f32 v59, v68, v69
	v_mul_f32_e32 v75, v77, v77
	v_cvt_pk_bf16_f32 v60, v78, v79
	v_cvt_pk_bf16_f32 v61, v70, v71
	global_load_dwordx4 v[62:65], v[72:73], off offset:256
	v_mul_f32_e32 v69, v69, v69
	v_mul_f32_e32 v77, v79, v79
	v_mul_f32_e32 v71, v71, v71
	v_fmac_f32_e32 v75, v76, v76
	v_fmac_f32_e32 v69, v68, v68
	v_fmac_f32_e32 v77, v78, v78
	v_fmac_f32_e32 v71, v70, v70
	v_add_f32_e32 v68, v75, v69
	v_add_f32_e32 v69, v77, v71
	v_add_f32_e32 v75, v68, v69
	global_store_dwordx4 v[72:73], v[58:61], off nt
	s_waitcnt vmcnt(1)
	v_lshlrev_b32_e32 v68, 16, v62
	v_and_b32_e32 v69, 0xffff0000, v62
	v_lshlrev_b32_e32 v62, 16, v63
	v_and_b32_e32 v63, 0xffff0000, v63
	v_lshlrev_b32_e32 v70, 16, v64
	v_and_b32_e32 v71, 0xffff0000, v64
	v_lshlrev_b32_e32 v64, 16, v65
	v_and_b32_e32 v65, 0xffff0000, v65
	v_pk_mul_f32 v[68:69], v[74:75], v[68:69] op_sel_hi:[0,1]
	v_pk_mul_f32 v[62:63], v[74:75], v[62:63] op_sel_hi:[0,1]
	v_pk_mul_f32 v[70:71], v[74:75], v[70:71] op_sel_hi:[0,1]
	v_pk_mul_f32 v[64:65], v[74:75], v[64:65] op_sel_hi:[0,1]
	v_pk_fma_f32 v[56:57], v[128:129], v[62:63], v[56:57]
	v_pk_fma_f32 v[54:55], v[124:125], v[68:69], v[54:55]
	v_pk_fma_f32 v[62:63], v[126:127], v[64:65], v[52:53]
	v_pk_fma_f32 v[64:65], v[122:123], v[70:71], v[50:51]
	v_mul_f32_e32 v50, v55, v55
	v_mul_f32_e32 v51, v57, v57
	v_mul_f32_e32 v52, v65, v65
	v_mul_f32_e32 v53, v63, v63
	v_fmac_f32_e32 v50, v54, v54
	v_fmac_f32_e32 v51, v56, v56
	v_fmac_f32_e32 v52, v64, v64
	v_fmac_f32_e32 v53, v62, v62
	v_add_f32_e32 v50, v50, v51
	v_add_f32_e32 v51, v52, v53
	v_add_f32_e32 v50, v50, v51
	v_add_f32_e32 v50, v75, v50
	ds_bpermute_b32 v51, v172, v50
	v_cvt_pk_bf16_f32 v52, v54, v55
	v_cvt_pk_bf16_f32 v53, v56, v57
	v_cvt_pk_bf16_f32 v54, v64, v65
	v_cvt_pk_bf16_f32 v55, v62, v63
	s_waitcnt lgkmcnt(0)
	v_add_f32_e32 v50, v50, v51
	ds_bpermute_b32 v51, v116, v50
	global_store_dwordx4 v[72:73], v[52:55], off offset:256 nt
	s_and_saveexec_b64 s[30:31], s[6:7]
	s_cbranch_execz .LBB0_1243
	v_lshlrev_b64 v[52:53], 6, v[66:67]
	v_lshl_add_u64 v[52:53], s[8:9], 0, v[52:53]
	v_lshl_add_u64 v[52:53], s[28:29], 2, v[52:53]
	s_lshl_b32 s16, s53, 2
	v_lshl_add_u64 v[52:53], v[52:53], 0, s[16:17]
	s_waitcnt lgkmcnt(0)
	v_add_f32_e32 v50, v50, v51
	global_store_dword v[52:53], v50, off
.LBB0_1243:
	s_or_b64 exec, exec, s[30:31]
	v_add_u32_e32 v50, 0x90, v154
	s_waitcnt lgkmcnt(0)
	v_ashrrev_i32_e32 v51, 31, v50
	v_lshlrev_b64 v[52:53], 11, v[50:51]
	v_lshl_add_u64 v[52:53], s[66:67], 0, v[52:53]
	v_lshl_add_u64 v[56:57], v[144:145], 1, v[52:53]
	global_load_dwordx4 v[52:55], v[56:57], off
	v_lshl_add_u64 v[58:59], v[50:51], 2, s[80:81]
	global_load_dword v58, v[58:59], off
	s_waitcnt vmcnt(1)
	v_lshlrev_b32_e32 v60, 16, v52
	v_and_b32_e32 v61, 0xffff0000, v52
	v_lshlrev_b32_e32 v52, 16, v53
	v_and_b32_e32 v53, 0xffff0000, v53
	v_lshlrev_b32_e32 v62, 16, v54
	v_and_b32_e32 v63, 0xffff0000, v54
	v_lshlrev_b32_e32 v54, 16, v55
	v_and_b32_e32 v55, 0xffff0000, v55
	s_waitcnt vmcnt(0)
	v_pk_mul_f32 v[60:61], v[58:59], v[60:61] op_sel_hi:[0,1]
	v_pk_mul_f32 v[52:53], v[58:59], v[52:53] op_sel_hi:[0,1]
	v_pk_mul_f32 v[62:63], v[58:59], v[62:63] op_sel_hi:[0,1]
	v_pk_mul_f32 v[54:55], v[58:59], v[54:55] op_sel_hi:[0,1]
	v_pk_fma_f32 v[52:53], v[152:153], v[52:53], v[48:49]
	v_pk_fma_f32 v[60:61], v[148:149], v[60:61], v[46:47]
	v_pk_fma_f32 v[54:55], v[150:151], v[54:55], v[44:45]
	v_pk_fma_f32 v[62:63], v[146:147], v[62:63], v[42:43]
	v_cvt_pk_bf16_f32 v42, v60, v61
	v_cvt_pk_bf16_f32 v43, v52, v53
	v_mul_f32_e32 v59, v61, v61
	v_cvt_pk_bf16_f32 v44, v62, v63
	v_cvt_pk_bf16_f32 v45, v54, v55
	global_load_dwordx4 v[46:49], v[56:57], off offset:256
	v_mul_f32_e32 v53, v53, v53
	v_mul_f32_e32 v61, v63, v63
	v_mul_f32_e32 v55, v55, v55
	v_fmac_f32_e32 v59, v60, v60
	v_fmac_f32_e32 v53, v52, v52
	v_fmac_f32_e32 v61, v62, v62
	v_fmac_f32_e32 v55, v54, v54
	v_add_f32_e32 v52, v59, v53
	v_add_f32_e32 v53, v61, v55
	v_add_f32_e32 v59, v52, v53
	global_store_dwordx4 v[56:57], v[42:45], off nt
	s_waitcnt vmcnt(1)
	v_lshlrev_b32_e32 v52, 16, v46
	v_and_b32_e32 v53, 0xffff0000, v46
	v_lshlrev_b32_e32 v46, 16, v47
	v_and_b32_e32 v47, 0xffff0000, v47
	v_lshlrev_b32_e32 v54, 16, v48
	v_and_b32_e32 v55, 0xffff0000, v48
	v_lshlrev_b32_e32 v48, 16, v49
	v_and_b32_e32 v49, 0xffff0000, v49
	v_pk_mul_f32 v[52:53], v[58:59], v[52:53] op_sel_hi:[0,1]
	v_pk_mul_f32 v[46:47], v[58:59], v[46:47] op_sel_hi:[0,1]
	v_pk_mul_f32 v[54:55], v[58:59], v[54:55] op_sel_hi:[0,1]
	v_pk_mul_f32 v[48:49], v[58:59], v[48:49] op_sel_hi:[0,1]
	v_pk_fma_f32 v[40:41], v[128:129], v[46:47], v[40:41]
	v_pk_fma_f32 v[38:39], v[124:125], v[52:53], v[38:39]
	v_pk_fma_f32 v[46:47], v[126:127], v[48:49], v[36:37]
	v_pk_fma_f32 v[48:49], v[122:123], v[54:55], v[34:35]
	v_mul_f32_e32 v34, v39, v39
	v_mul_f32_e32 v35, v41, v41
	v_mul_f32_e32 v36, v49, v49
	v_mul_f32_e32 v37, v47, v47
	v_fmac_f32_e32 v34, v38, v38
	v_fmac_f32_e32 v35, v40, v40
	v_fmac_f32_e32 v36, v48, v48
	v_fmac_f32_e32 v37, v46, v46
	v_add_f32_e32 v34, v34, v35
	v_add_f32_e32 v35, v36, v37
	v_add_f32_e32 v34, v34, v35
	v_add_f32_e32 v34, v59, v34
	ds_bpermute_b32 v35, v172, v34
	v_cvt_pk_bf16_f32 v36, v38, v39
	v_cvt_pk_bf16_f32 v37, v40, v41
	v_cvt_pk_bf16_f32 v38, v48, v49
	v_cvt_pk_bf16_f32 v39, v46, v47
	s_waitcnt lgkmcnt(0)
	v_add_f32_e32 v34, v34, v35
	ds_bpermute_b32 v35, v116, v34
	global_store_dwordx4 v[56:57], v[36:39], off offset:256 nt
	s_and_saveexec_b64 s[30:31], s[6:7]
	s_cbranch_execz .LBB0_1245
	v_lshlrev_b64 v[36:37], 6, v[50:51]
	v_lshl_add_u64 v[36:37], s[8:9], 0, v[36:37]
	v_lshl_add_u64 v[36:37], s[28:29], 2, v[36:37]
	s_lshl_b32 s16, s53, 2
	v_lshl_add_u64 v[36:37], v[36:37], 0, s[16:17]
	s_waitcnt lgkmcnt(0)
	v_add_f32_e32 v34, v34, v35
	global_store_dword v[36:37], v34, off
; __device__ __forceinline__ unsigned cvt_pk_bf16(float lo, float hi) { unsigned r; asm volatile("v_cvt_pk_bf16_f32 %0, %1, %2" : "=v"(r) : "v"(lo), "v"(hi)); return r; }
;     __device__ __forceinline__ void operator()(const f32x4 (&acc)[2][2][4][2], const Unit& u, int wr, int wc, int fr, int fq) const {
;     ...
;         for (int ai = 0; ai < 2; ++ai)
; #pragma unroll
;             for (int m = 0; m < 4; ++m) { const int r = rowt + ai * HALF + wr * 64 + m * 16 + fr; const size_t off = (size_t)r * 1024 + col0; float ss = 0.f;
;                 float xi = 0.f; if constexpr (RECON) xi = xinv[r];
; #pragma unroll
;                 for (int bj = 0; bj < 2; ++bj) { f32x4 b0, b1;
;                     if constexpr (RECON) { const u32x4 w = *(const u32x4*)(xb + off + bj * HALF);
;                         b0 = (f32x4){__builtin_bit_cast(float, w.x << 16), __builtin_bit_cast(float, w.x & 0xffff0000u), __builtin_bit_cast(float, w.y << 16), __builtin_bit_cast(float, w.y & 0xffff0000u)} * xi * gi[bj][0];
;                         b1 = (f32x4){__builtin_bit_cast(float, w.z << 16), __builtin_bit_cast(float, w.z & 0xffff0000u), __builtin_bit_cast(float, w.w << 16), __builtin_bit_cast(float, w.w & 0xffff0000u)} * xi * gi[bj][1]; }
;                     else { b0 = *(const f32x4*)(base + off + bj * HALF); b1 = *(const f32x4*)(base + off + bj * HALF + 4); }
;                     const f32x4 o0 = b0 + acc[ai][bj][m][0], o1 = b1 + acc[ai][bj][m][1];
;                     ss += ((o0[0] * o0[0] + o0[1] * o0[1]) + (o0[2] * o0[2] + o0[3] * o0[3])) + ((o1[0] * o1[0] + o1[1] * o1[1]) + (o1[2] * o1[2] + o1[3] * o1[3]));
;                     u32x4 w2; w2.x = cvt_pk_bf16(o0[0], o0[1]); w2.y = cvt_pk_bf16(o0[2], o0[3]); w2.z = cvt_pk_bf16(o1[0], o1[1]); w2.w = cvt_pk_bf16(o1[2], o1[3]); *(u32x4*)(xb + off + bj * HALF) = w2; }
;                 ss += __shfl_xor(ss, 16); ss += __shfl_xor(ss, 32);
;                 if (fq == 0) stats[(size_t)r * 16 + u.pn * 4 + wc] = ss;
.LBB0_1245:
	s_or_b64 exec, exec, s[30:31]
	v_add_u32_e32 v34, 0xa0, v154
	s_waitcnt lgkmcnt(0)
	v_ashrrev_i32_e32 v35, 31, v34
	v_lshlrev_b64 v[36:37], 11, v[34:35]
	v_lshl_add_u64 v[36:37], s[66:67], 0, v[36:37]
	v_lshl_add_u64 v[40:41], v[144:145], 1, v[36:37]
	global_load_dwordx4 v[36:39], v[40:41], off
	v_lshl_add_u64 v[42:43], v[34:35], 2, s[80:81]
	global_load_dword v42, v[42:43], off
	s_waitcnt vmcnt(1)
	v_lshlrev_b32_e32 v44, 16, v36
	v_and_b32_e32 v45, 0xffff0000, v36
	v_lshlrev_b32_e32 v36, 16, v37
	v_and_b32_e32 v37, 0xffff0000, v37
	v_lshlrev_b32_e32 v46, 16, v38
	v_and_b32_e32 v47, 0xffff0000, v38
	v_lshlrev_b32_e32 v38, 16, v39
	v_and_b32_e32 v39, 0xffff0000, v39
	s_waitcnt vmcnt(0)
	v_pk_mul_f32 v[44:45], v[42:43], v[44:45] op_sel_hi:[0,1]
	v_pk_mul_f32 v[36:37], v[42:43], v[36:37] op_sel_hi:[0,1]
	v_pk_mul_f32 v[46:47], v[42:43], v[46:47] op_sel_hi:[0,1]
	v_pk_mul_f32 v[38:39], v[42:43], v[38:39] op_sel_hi:[0,1]
	v_pk_fma_f32 v[36:37], v[152:153], v[36:37], v[32:33]
	v_pk_fma_f32 v[44:45], v[148:149], v[44:45], v[30:31]
	v_pk_fma_f32 v[38:39], v[150:151], v[38:39], v[28:29]
	v_pk_fma_f32 v[46:47], v[146:147], v[46:47], v[26:27]
	v_cvt_pk_bf16_f32 v26, v44, v45
	v_cvt_pk_bf16_f32 v27, v36, v37
	v_mul_f32_e32 v43, v45, v45
	v_cvt_pk_bf16_f32 v28, v46, v47
	v_cvt_pk_bf16_f32 v29, v38, v39
	global_load_dwordx4 v[30:33], v[40:41], off offset:256
	v_mul_f32_e32 v37, v37, v37
	v_mul_f32_e32 v45, v47, v47
	v_mul_f32_e32 v39, v39, v39
	v_fmac_f32_e32 v43, v44, v44
	v_fmac_f32_e32 v37, v36, v36
	v_fmac_f32_e32 v45, v46, v46
	v_fmac_f32_e32 v39, v38, v38
	v_add_f32_e32 v36, v43, v37
	v_add_f32_e32 v37, v45, v39
	v_add_f32_e32 v43, v36, v37
	global_store_dwordx4 v[40:41], v[26:29], off nt
	s_waitcnt vmcnt(1)
	v_lshlrev_b32_e32 v36, 16, v30
	v_and_b32_e32 v37, 0xffff0000, v30
	v_lshlrev_b32_e32 v30, 16, v31
	v_and_b32_e32 v31, 0xffff0000, v31
	v_lshlrev_b32_e32 v38, 16, v32
	v_and_b32_e32 v39, 0xffff0000, v32
	v_lshlrev_b32_e32 v32, 16, v33
	v_and_b32_e32 v33, 0xffff0000, v33
	v_pk_mul_f32 v[36:37], v[42:43], v[36:37] op_sel_hi:[0,1]
	v_pk_mul_f32 v[30:31], v[42:43], v[30:31] op_sel_hi:[0,1]
	v_pk_mul_f32 v[38:39], v[42:43], v[38:39] op_sel_hi:[0,1]
	v_pk_mul_f32 v[32:33], v[42:43], v[32:33] op_sel_hi:[0,1]
	v_pk_fma_f32 v[24:25], v[128:129], v[30:31], v[24:25]
	v_pk_fma_f32 v[22:23], v[124:125], v[36:37], v[22:23]
	v_pk_fma_f32 v[30:31], v[126:127], v[32:33], v[20:21]
	v_pk_fma_f32 v[32:33], v[122:123], v[38:39], v[18:19]
	v_mul_f32_e32 v18, v23, v23
	v_mul_f32_e32 v19, v25, v25
	v_mul_f32_e32 v20, v33, v33
	v_mul_f32_e32 v21, v31, v31
	v_fmac_f32_e32 v18, v22, v22
	v_fmac_f32_e32 v19, v24, v24
	v_fmac_f32_e32 v20, v32, v32
	v_fmac_f32_e32 v21, v30, v30
	v_add_f32_e32 v18, v18, v19
	v_add_f32_e32 v19, v20, v21
	v_add_f32_e32 v18, v18, v19
	v_add_f32_e32 v18, v43, v18
	ds_bpermute_b32 v19, v172, v18
	v_cvt_pk_bf16_f32 v20, v22, v23
	v_cvt_pk_bf16_f32 v21, v24, v25
	v_cvt_pk_bf16_f32 v22, v32, v33
	v_cvt_pk_bf16_f32 v23, v30, v31
	s_waitcnt lgkmcnt(0)
	v_add_f32_e32 v18, v18, v19
	ds_bpermute_b32 v19, v116, v18
	global_store_dwordx4 v[40:41], v[20:23], off offset:256 nt
	s_and_saveexec_b64 s[30:31], s[6:7]
	s_cbranch_execz .LBB0_1247
	v_lshlrev_b64 v[20:21], 6, v[34:35]
	v_lshl_add_u64 v[20:21], s[8:9], 0, v[20:21]
	v_lshl_add_u64 v[20:21], s[28:29], 2, v[20:21]
	s_lshl_b32 s16, s53, 2
	v_lshl_add_u64 v[20:21], v[20:21], 0, s[16:17]
	s_waitcnt lgkmcnt(0)
	v_add_f32_e32 v18, v18, v19
	global_store_dword v[20:21], v18, off
.LBB0_1247:
	s_or_b64 exec, exec, s[30:31]
	v_add_u32_e32 v18, 0xb0, v154
	s_waitcnt lgkmcnt(0)
	v_ashrrev_i32_e32 v19, 31, v18
	v_lshlrev_b64 v[20:21], 11, v[18:19]
	v_lshl_add_u64 v[20:21], s[66:67], 0, v[20:21]
	v_lshl_add_u64 v[24:25], v[144:145], 1, v[20:21]
	global_load_dwordx4 v[20:23], v[24:25], off
	v_lshl_add_u64 v[26:27], v[18:19], 2, s[80:81]
	global_load_dword v26, v[26:27], off
	s_waitcnt vmcnt(1)
	v_lshlrev_b32_e32 v28, 16, v20
	v_and_b32_e32 v29, 0xffff0000, v20
	v_lshlrev_b32_e32 v20, 16, v21
	v_and_b32_e32 v21, 0xffff0000, v21
	v_lshlrev_b32_e32 v30, 16, v22
	v_and_b32_e32 v31, 0xffff0000, v22
	v_lshlrev_b32_e32 v22, 16, v23
	v_and_b32_e32 v23, 0xffff0000, v23
	s_waitcnt vmcnt(0)
	v_pk_mul_f32 v[28:29], v[26:27], v[28:29] op_sel_hi:[0,1]
	v_pk_mul_f32 v[20:21], v[26:27], v[20:21] op_sel_hi:[0,1]
	v_pk_mul_f32 v[30:31], v[26:27], v[30:31] op_sel_hi:[0,1]
	v_pk_mul_f32 v[22:23], v[26:27], v[22:23] op_sel_hi:[0,1]
	v_pk_fma_f32 v[20:21], v[152:153], v[20:21], v[16:17]
	v_pk_fma_f32 v[28:29], v[148:149], v[28:29], v[14:15]
	v_pk_fma_f32 v[22:23], v[150:151], v[22:23], v[12:13]
	v_pk_fma_f32 v[30:31], v[146:147], v[30:31], v[10:11]
	v_cvt_pk_bf16_f32 v10, v28, v29
	v_cvt_pk_bf16_f32 v11, v20, v21
	v_mul_f32_e32 v27, v29, v29
	v_cvt_pk_bf16_f32 v12, v30, v31
	v_cvt_pk_bf16_f32 v13, v22, v23
	global_load_dwordx4 v[14:17], v[24:25], off offset:256
	v_mul_f32_e32 v21, v21, v21
	v_mul_f32_e32 v29, v31, v31
	v_mul_f32_e32 v23, v23, v23
	v_fmac_f32_e32 v27, v28, v28
	v_fmac_f32_e32 v21, v20, v20
	v_fmac_f32_e32 v29, v30, v30
	v_fmac_f32_e32 v23, v22, v22
	v_add_f32_e32 v20, v27, v21
	v_add_f32_e32 v21, v29, v23
	v_add_f32_e32 v27, v20, v21
	global_store_dwordx4 v[24:25], v[10:13], off nt
	s_waitcnt vmcnt(1)
	v_lshlrev_b32_e32 v20, 16, v14
	v_and_b32_e32 v21, 0xffff0000, v14
	v_lshlrev_b32_e32 v14, 16, v15
	v_and_b32_e32 v15, 0xffff0000, v15
	v_lshlrev_b32_e32 v22, 16, v16
	v_and_b32_e32 v23, 0xffff0000, v16
	v_lshlrev_b32_e32 v16, 16, v17
	v_and_b32_e32 v17, 0xffff0000, v17
	v_pk_mul_f32 v[20:21], v[26:27], v[20:21] op_sel_hi:[0,1]
	v_pk_mul_f32 v[14:15], v[26:27], v[14:15] op_sel_hi:[0,1]
	v_pk_mul_f32 v[22:23], v[26:27], v[22:23] op_sel_hi:[0,1]
	v_pk_mul_f32 v[16:17], v[26:27], v[16:17] op_sel_hi:[0,1]
	v_pk_fma_f32 v[8:9], v[128:129], v[14:15], v[8:9]
	v_pk_fma_f32 v[6:7], v[124:125], v[20:21], v[6:7]
	v_pk_fma_f32 v[14:15], v[126:127], v[16:17], v[4:5]
	v_pk_fma_f32 v[16:17], v[122:123], v[22:23], v[2:3]
	v_mul_f32_e32 v2, v7, v7
	v_mul_f32_e32 v3, v9, v9
	v_mul_f32_e32 v4, v17, v17
	v_mul_f32_e32 v5, v15, v15
	v_fmac_f32_e32 v2, v6, v6
	v_fmac_f32_e32 v3, v8, v8
	v_fmac_f32_e32 v4, v16, v16
	v_fmac_f32_e32 v5, v14, v14
	v_add_f32_e32 v2, v2, v3
	v_add_f32_e32 v3, v4, v5
	v_add_f32_e32 v2, v2, v3
	v_add_f32_e32 v2, v27, v2
	ds_bpermute_b32 v3, v172, v2
	v_cvt_pk_bf16_f32 v4, v6, v7
	v_cvt_pk_bf16_f32 v5, v8, v9
	v_cvt_pk_bf16_f32 v6, v16, v17
	v_cvt_pk_bf16_f32 v7, v14, v15
	s_waitcnt lgkmcnt(0)
	v_add_f32_e32 v2, v2, v3
	ds_bpermute_b32 v3, v116, v2
	global_store_dwordx4 v[24:25], v[4:7], off offset:256 nt
	s_and_saveexec_b64 s[30:31], s[6:7]
	s_cbranch_execz .LBB0_1249
	v_lshlrev_b64 v[4:5], 6, v[18:19]
	v_lshl_add_u64 v[4:5], s[8:9], 0, v[4:5]
	v_lshl_add_u64 v[4:5], s[28:29], 2, v[4:5]
	s_lshl_b32 s16, s53, 2
	v_lshl_add_u64 v[4:5], v[4:5], 0, s[16:17]
	s_waitcnt lgkmcnt(0)
	v_add_f32_e32 v2, v2, v3
	global_store_dword v[4:5], v2, off
